# m5_attn_pipe_trip0
# baseline (speedup 1.0000x reference)
.LBB0_186:
	v_mfma_f32_32x32x16_bf16 v[50:65], v[118:121], v[150:153], v[50:65]
	ds_read_b128 v[182:185], v169 offset:16384
	ds_read_b128 v[198:201], v170 offset:16384
	ds_read_b128 v[202:205], v171 offset:16384
	v_exp_f32_e32 v226, v82
	s_add_i32 s0, s97, 0xfffffec0
	s_and_b32 s0, s0, 0xfc0
	v_or_b32_e32 v66, s0, v166
	v_sub_u32_e32 v66, v167, v66
	v_cvt_f32_i32_e32 v67, v66
	s_cmp_lt_u32 s0, s84
	s_cselect_b64 s[42:43], -1, 0
	v_mfma_f32_32x32x16_bf16 v[34:49], v[134:137], v[150:153], v[34:49]
	ds_read_b128 v[206:209], v172 offset:16384
	ds_read_b64_tr_b16 v[118:119], v179 offset:8192
	ds_read_b64_tr_b16 v[120:121], v180 offset:8192
	v_exp_f32_e32 v227, v83
	v_fma_f32 v80, -v158, |v67|, -v0
	s_cmp_lg_u32 s0, s84
	v_mfma_f32_32x32x16_bf16 v[18:33], v[138:141], v[150:153], v[18:33]
	ds_read_b64_tr_b16 v[134:135], v175 offset:12288
	ds_read_b64_tr_b16 v[136:137], v176 offset:12288
	ds_read_b64_tr_b16 v[138:139], v177 offset:12288
	v_exp_f32_e32 v239, v84
	v_mfma_f32_32x32x16_bf16 v[2:17], v[142:145], v[150:153], v[2:17]
	ds_read_b64_tr_b16 v[140:141], v178 offset:12288
	ds_read_b64_tr_b16 v[142:143], v179 offset:12288
	ds_read_b64_tr_b16 v[144:145], v180 offset:12288
	v_exp_f32_e32 v240, v85
	v_lshl_add_u64 v[250:251], v[248:249], 0, s[56:57]
	s_mov_b32 m0, s100
	s_nop 0
	global_load_lds_dwordx4 v[250:251], off
	v_mfma_f32_32x32x16_bf16 v[50:65], v[122:125], v[146:149], v[50:65]
	ds_read_b64_tr_b16 v[122:123], v177 offset:8192
	ds_read_b64_tr_b16 v[124:125], v178 offset:8192
	v_exp_f32_e32 v241, v86
	v_mfma_f32_32x32x16_bf16 v[34:49], v[130:133], v[146:149], v[34:49]
	ds_read_b64_tr_b16 v[130:131], v173 offset:8192
	ds_read_b64_tr_b16 v[132:133], v174 offset:8192
	v_exp_f32_e32 v164, v87
	v_mfma_f32_32x32x16_bf16 v[18:33], v[126:129], v[146:149], v[18:33]
	ds_read_b64_tr_b16 v[126:127], v175 offset:8192
	ds_read_b64_tr_b16 v[128:129], v176 offset:8192
	v_exp_f32_e32 v242, v88
	v_mfma_f32_32x32x16_bf16 v[2:17], v[114:117], v[146:149], v[2:17]
	ds_read_b64_tr_b16 v[114:115], v173 offset:12288
	ds_read_b64_tr_b16 v[116:117], v174 offset:12288
	v_exp_f32_e32 v243, v89
	s_cbranch_scc1 .LBB0_188
	v_add_u32_e32 v67, -2, v66
	v_cvt_f32_i32_e32 v67, v67
	v_add_u32_e32 v68, -1, v66
	v_cvt_f32_i32_e32 v68, v68
	v_add_u32_e32 v70, -8, v66
	v_and_b32_e32 v69, 0x7fffffff, v67
	v_add_u32_e32 v67, -3, v66
	v_cvt_f32_i32_e32 v67, v67
	v_cvt_f32_i32_e32 v70, v70
	v_and_b32_e32 v68, 0x7fffffff, v68
	v_pk_fma_f32 v[210:211], v[162:163], v[68:69], v[0:1] op_sel_hi:[1,1,0] neg_lo:[0,0,1] neg_hi:[0,0,1]
	v_and_b32_e32 v68, 0x7fffffff, v67
	v_add_u32_e32 v67, -10, v66
	v_cvt_f32_i32_e32 v67, v67
	v_and_b32_e32 v69, 0x7fffffff, v70
	v_pk_fma_f32 v[212:213], v[162:163], v[68:69], v[0:1] op_sel_hi:[1,1,0] neg_lo:[0,0,1] neg_hi:[0,0,1]
	v_add_u32_e32 v68, -9, v66
	v_cvt_f32_i32_e32 v68, v68
	v_and_b32_e32 v69, 0x7fffffff, v67
	v_add_u32_e32 v67, -16, v66
	v_cvt_f32_i32_e32 v67, v67
	v_add_u32_e32 v70, -11, v66
	v_cvt_f32_i32_e32 v70, v70
	v_and_b32_e32 v68, 0x7fffffff, v68
	v_pk_fma_f32 v[214:215], v[162:163], v[68:69], v[0:1] op_sel_hi:[1,1,0] neg_lo:[0,0,1] neg_hi:[0,0,1]
	v_and_b32_e32 v69, 0x7fffffff, v67
	v_subrev_u32_e32 v67, 18, v66
	v_cvt_f32_i32_e32 v67, v67
	v_and_b32_e32 v68, 0x7fffffff, v70
	v_pk_fma_f32 v[216:217], v[162:163], v[68:69], v[0:1] op_sel_hi:[1,1,0] neg_lo:[0,0,1] neg_hi:[0,0,1]
	v_subrev_u32_e32 v68, 17, v66
	v_cvt_f32_i32_e32 v68, v68
	v_and_b32_e32 v69, 0x7fffffff, v67
	v_subrev_u32_e32 v67, 24, v66
	v_subrev_u32_e32 v70, 19, v66
	v_cvt_f32_i32_e32 v67, v67
	v_cvt_f32_i32_e32 v70, v70
	v_and_b32_e32 v68, 0x7fffffff, v68
	v_pk_fma_f32 v[218:219], v[162:163], v[68:69], v[0:1] op_sel_hi:[1,1,0] neg_lo:[0,0,1] neg_hi:[0,0,1]
	v_and_b32_e32 v69, 0x7fffffff, v67
	v_and_b32_e32 v68, 0x7fffffff, v70
	v_pk_fma_f32 v[220:221], v[162:163], v[68:69], v[0:1] op_sel_hi:[1,1,0] neg_lo:[0,0,1] neg_hi:[0,0,1]
	v_subrev_u32_e32 v67, 26, v66
	v_subrev_u32_e32 v68, 25, v66
	v_cvt_f32_i32_e32 v67, v67
	v_cvt_f32_i32_e32 v68, v68
	v_subrev_u32_e32 v66, 27, v66
	v_cvt_f32_i32_e32 v69, v66
	v_and_b32_e32 v67, 0x7fffffff, v67
	v_and_b32_e32 v66, 0x7fffffff, v68
	v_mov_b32_e32 v81, v210
	v_pk_fma_f32 v[222:223], v[162:163], v[66:67], v[0:1] op_sel_hi:[1,1,0] neg_lo:[0,0,1] neg_hi:[0,0,1]
	v_fma_f32 v224, -v158, |v69|, -v0
	v_mov_b64_e32 v[66:67], v[80:81]
	v_mov_b64_e32 v[68:69], v[82:83]
	v_mov_b64_e32 v[70:71], v[84:85]
	v_mov_b64_e32 v[72:73], v[86:87]
	v_mov_b64_e32 v[74:75], v[88:89]
	v_mov_b64_e32 v[76:77], v[90:91]
	v_mov_b64_e32 v[78:79], v[92:93]
	v_mov_b64_e32 v[80:81], v[94:95]
	v_mov_b32_e32 v68, v211
	v_mov_b32_e32 v69, v212
	v_mov_b32_e32 v70, v213
	v_mov_b32_e32 v71, v214
	v_mov_b32_e32 v72, v215
	v_mov_b32_e32 v73, v216
	v_mov_b32_e32 v74, v217
	v_mov_b32_e32 v75, v218
	v_mov_b32_e32 v76, v219
	v_mov_b32_e32 v77, v220
	v_mov_b32_e32 v78, v221
	v_mov_b32_e32 v79, v222
	v_mov_b32_e32 v80, v223
	v_mov_b32_e32 v81, v224
	s_branch .LBB0_189

.LBB0_189:
	v_lshl_add_u64 v[250:251], v[248:249], 0, s[68:69]
	s_add_i32 m0, s85, 0x1c000
	s_nop 0
	global_load_lds_dwordx4 v[250:251], off
	v_add_f32_e32 v147, v247, v181
	s_waitcnt lgkmcnt(0)
	v_mfma_f32_32x32x16_bf16 v[66:81], v[182:185], v[98:101], v[66:81]
	v_exp_f32_e32 v183, v90
	v_exp_f32_e32 v184, v91
	v_add_f32_e32 v146, 0, v226
	v_add_f32_e32 v146, v227, v146
	v_exp_f32_e32 v185, v92
	v_mfma_f32_32x32x16_bf16 v[66:81], v[198:201], v[102:105], v[66:81]
	v_exp_f32_e32 v198, v93
	v_add_f32_e32 v146, v239, v146
	v_add_f32_e32 v146, v240, v146
	v_exp_f32_e32 v199, v94
	v_add_f32_e32 v146, v241, v146
	v_mfma_f32_32x32x16_bf16 v[66:81], v[202:205], v[106:109], v[66:81]
	v_exp_f32_e32 v200, v95
	v_add_f32_e32 v146, v164, v146
	v_add_f32_e32 v146, v242, v146
	v_exp_f32_e32 v201, v96
	v_add_f32_e32 v146, v243, v146
	v_mfma_f32_32x32x16_bf16 v[66:81], v[206:209], v[110:113], v[66:81]
	v_exp_f32_e32 v202, v97
	v_add_f32_e32 v146, v183, v146
	v_add_f32_e32 v146, v184, v146
	v_add_f32_e32 v146, v185, v146
	v_add_f32_e32 v146, v198, v146
	v_add_f32_e32 v146, v199, v146
	v_add_f32_e32 v146, v200, v146
	v_add_f32_e32 v146, v201, v146
	v_add_f32_e32 v148, v202, v146
	v_cmp_nge_f32_e32 vcc, s12, v148
	s_cbranch_vccz .LBB0_191
	v_max_f32_e32 v146, v83, v83
	v_max_f32_e32 v148, v82, v82
	v_max_f32_e32 v146, v148, v146
	v_max3_f32 v146, v146, v84, v85
	v_max3_f32 v146, v146, v86, v87
	v_max3_f32 v146, v146, v88, v89
	v_max3_f32 v146, v146, v90, v91
	v_max3_f32 v146, v146, v92, v93
	v_max3_f32 v146, v146, v94, v95
	v_max3_f32 v146, v146, v96, v97
	ds_bpermute_b32 v148, v159, v146
	s_waitcnt lgkmcnt(0)
	v_max3_f32 v148, v146, v148, 0
	v_sub_f32_e32 v82, v82, v148
	v_exp_f32_e32 v82, v82
	v_sub_f32_e32 v83, v83, v148
	v_exp_f32_e32 v83, v83
	v_sub_f32_e32 v84, v84, v148
	v_exp_f32_e32 v84, v84
	v_sub_f32_e32 v85, v85, v148
	v_exp_f32_e32 v85, v85
	v_sub_f32_e32 v86, v86, v148
	v_sub_f32_e32 v87, v87, v148
	v_add_f32_e32 v149, 0, v82
	v_exp_f32_e32 v86, v86
	v_exp_f32_e32 v87, v87
	v_add_f32_e32 v149, v83, v149
	v_sub_f32_e32 v88, v88, v148
	v_sub_f32_e32 v89, v89, v148
	v_add_f32_e32 v149, v84, v149
	v_exp_f32_e32 v88, v88
	v_exp_f32_e32 v89, v89
	v_add_f32_e32 v149, v85, v149
	v_add_f32_e32 v149, v86, v149
	v_cvt_pk_bf16_f32 v82, v82, v83
	v_cvt_pk_bf16_f32 v83, v84, v85
	v_cvt_pk_bf16_f32 v84, v86, v87
	v_sub_f32_e32 v86, v90, v148
	v_add_f32_e32 v149, v87, v149
	v_exp_f32_e32 v86, v86
	v_sub_f32_e32 v87, v91, v148
	v_add_f32_e32 v149, v88, v149
	v_cvt_pk_bf16_f32 v85, v88, v89
	v_exp_f32_e32 v87, v87
	v_sub_f32_e32 v88, v92, v148
	v_add_f32_e32 v149, v89, v149
	v_exp_f32_e32 v88, v88
	v_sub_f32_e32 v89, v93, v148
	v_exp_f32_e32 v89, v89
	v_sub_f32_e32 v91, v94, v148
	v_add_f32_e32 v90, v86, v149
	v_exp_f32_e32 v91, v91
	v_sub_f32_e32 v92, v95, v148
	v_add_f32_e32 v90, v87, v90
	v_exp_f32_e32 v92, v92
	v_sub_f32_e32 v93, v96, v148
	v_add_f32_e32 v90, v88, v90
	v_exp_f32_e32 v93, v93
	v_sub_f32_e32 v94, v97, v148
	v_exp_f32_e64 v146, -v148
	v_add_f32_e32 v90, v89, v90
	v_exp_f32_e32 v94, v94
	v_add_f32_e32 v90, v91, v90
	v_add_f32_e32 v90, v92, v90
	v_add_f32_e32 v0, v0, v148
	v_add_f32_e32 v90, v93, v90
	v_pk_mul_f32 v[64:65], v[64:65], v[146:147] op_sel_hi:[1,0]
	v_pk_mul_f32 v[62:63], v[62:63], v[146:147] op_sel_hi:[1,0]
	v_pk_mul_f32 v[60:61], v[60:61], v[146:147] op_sel_hi:[1,0]
	v_pk_mul_f32 v[58:59], v[58:59], v[146:147] op_sel_hi:[1,0]
	v_pk_mul_f32 v[56:57], v[56:57], v[146:147] op_sel_hi:[1,0]
	v_pk_mul_f32 v[54:55], v[54:55], v[146:147] op_sel_hi:[1,0]
	v_pk_mul_f32 v[52:53], v[52:53], v[146:147] op_sel_hi:[1,0]
	v_pk_mul_f32 v[50:51], v[50:51], v[146:147] op_sel_hi:[1,0]
	v_pk_mul_f32 v[48:49], v[48:49], v[146:147] op_sel_hi:[1,0]
	v_pk_mul_f32 v[46:47], v[46:47], v[146:147] op_sel_hi:[1,0]
	v_pk_mul_f32 v[44:45], v[44:45], v[146:147] op_sel_hi:[1,0]
	v_pk_mul_f32 v[42:43], v[42:43], v[146:147] op_sel_hi:[1,0]
	v_pk_mul_f32 v[40:41], v[40:41], v[146:147] op_sel_hi:[1,0]
	v_pk_mul_f32 v[38:39], v[38:39], v[146:147] op_sel_hi:[1,0]
	v_pk_mul_f32 v[36:37], v[36:37], v[146:147] op_sel_hi:[1,0]
	v_pk_mul_f32 v[34:35], v[34:35], v[146:147] op_sel_hi:[1,0]
	v_pk_mul_f32 v[32:33], v[32:33], v[146:147] op_sel_hi:[1,0]
	v_pk_mul_f32 v[30:31], v[30:31], v[146:147] op_sel_hi:[1,0]
	v_pk_mul_f32 v[28:29], v[28:29], v[146:147] op_sel_hi:[1,0]
	v_pk_mul_f32 v[26:27], v[26:27], v[146:147] op_sel_hi:[1,0]
	v_pk_mul_f32 v[24:25], v[24:25], v[146:147] op_sel_hi:[1,0]
	v_pk_mul_f32 v[22:23], v[22:23], v[146:147] op_sel_hi:[1,0]
	v_pk_mul_f32 v[20:21], v[20:21], v[146:147] op_sel_hi:[1,0]
	v_pk_mul_f32 v[18:19], v[18:19], v[146:147] op_sel_hi:[1,0]
	v_pk_mul_f32 v[16:17], v[16:17], v[146:147] op_sel_hi:[1,0]
	v_pk_mul_f32 v[14:15], v[14:15], v[146:147] op_sel_hi:[1,0]
	v_pk_mul_f32 v[12:13], v[12:13], v[146:147] op_sel_hi:[1,0]
	v_pk_mul_f32 v[10:11], v[10:11], v[146:147] op_sel_hi:[1,0]
	v_pk_mul_f32 v[8:9], v[8:9], v[146:147] op_sel_hi:[1,0]
	v_pk_mul_f32 v[6:7], v[6:7], v[146:147] op_sel_hi:[1,0]
	v_pk_mul_f32 v[4:5], v[4:5], v[146:147] op_sel_hi:[1,0]
	v_pk_mul_f32 v[2:3], v[2:3], v[146:147] op_sel_hi:[1,0]
	v_sub_f32_e32 v81, v81, v148
	v_sub_f32_e32 v80, v80, v148
	v_sub_f32_e32 v79, v79, v148
	v_sub_f32_e32 v78, v78, v148
	v_sub_f32_e32 v77, v77, v148
	v_sub_f32_e32 v76, v76, v148
	v_sub_f32_e32 v75, v75, v148
	v_sub_f32_e32 v74, v74, v148
	v_sub_f32_e32 v73, v73, v148
	v_sub_f32_e32 v72, v72, v148
	v_sub_f32_e32 v71, v71, v148
	v_sub_f32_e32 v70, v70, v148
	v_sub_f32_e32 v69, v69, v148
	v_sub_f32_e32 v68, v68, v148
	v_sub_f32_e32 v67, v67, v148
	v_sub_f32_e32 v66, v66, v148
	v_add_f32_e32 v148, v94, v90
	v_cvt_pk_bf16_f32 v86, v86, v87
	v_cvt_pk_bf16_f32 v87, v88, v89
	v_cvt_pk_bf16_f32 v88, v91, v92
	v_cvt_pk_bf16_f32 v89, v93, v94
	v_mul_f32_e32 v147, v147, v146
	v_xor_b32_e32 v146, 0x80000000, v0
	s_branch .LBB0_192
.LBB0_191:
	v_xor_b32_e32 v146, 0x80000000, v0
	v_cvt_pk_bf16_f32 v82, v226, v227
	v_cvt_pk_bf16_f32 v83, v239, v240
	v_cvt_pk_bf16_f32 v84, v241, v164
	v_cvt_pk_bf16_f32 v85, v242, v243
	v_cvt_pk_bf16_f32 v86, v183, v184
	v_cvt_pk_bf16_f32 v87, v185, v198
	v_cvt_pk_bf16_f32 v88, v199, v200
	v_cvt_pk_bf16_f32 v89, v201, v202
